# out-projection epilogue rewritten: residual-x loads issued 7 chunks ahead, each load covers 8 rows x one full 128-B line, halves routed to their owner lanes inside the f32 add (DPP row_ror:8 + bank ma
# speedup vs baseline: 1.0229x; 1.0051x over previous
; __device__ __forceinline__ unsigned cvt_pk_bf16(float lo, float hi) { unsigned r; asm volatile("v_cvt_pk_bf16_f32 %0, %1, %2" : "=v"(r) : "v"(lo), "v"(hi)); return r; }
;     __device__ __forceinline__ void operator()(const f32x4 (&acc)[2][2][4][2], const Unit& u, int wr, int wc, int fr, int fq) const {
; #pragma unroll
;         for (int ai = 0; ai < 2; ++ai)
; #pragma unroll
;             for (int m = 0; m < 4; ++m) {
;                 const int row = u.pm * BM + ai * HALF + wr * 64 + m * 16 + fr;
;                 const float* xr = xrow(xp, xs, row);
; #pragma unroll
;                 for (int bj = 0; bj < 2; ++bj) {
;                     const int col = u.pn * BM + bj * HALF + wc * 32 + 8 * fq;
;                     const f32x4 x0 = *(const f32x4*)(xr + col), x1v = *(const f32x4*)(xr + col + 4);
;                     const f32x4 v0 = acc[ai][bj][m][0] + x0, v1 = acc[ai][bj][m][1] + x1v;
;                     u32x4 w; w.x = cvt_pk_bf16(v0[0], v0[1]); w.y = cvt_pk_bf16(v0[2], v0[3]); w.z = cvt_pk_bf16(v1[0], v1[1]); w.w = cvt_pk_bf16(v1[2], v1[3]);
;                     *(u32x4*)(X1B + (size_t)row * D + col) = w;
;                 }
;             }
.LBB0_516:
	v_lshl_add_u32 v144, s26, 8, v150
	v_lshl_or_b32 v146, s48, 8, v152
	v_ashrrev_i32_e32 v147, 31, v146
	v_lshlrev_b64 v[148:149], 2, v[146:147]
	v_lshlrev_b64 v[146:147], 1, v[146:147]
	v_and_b32_e32 v253, 8, v193
	v_lshl_add_u32 v148, v253, 1, v148
	v_sub_u32_e32 v253, v144, v253
	v_mov_b32_e32 v226, s19
	v_mov_b32_e32 v227, s17
	v_mov_b32_e32 v190, s18
	v_mov_b32_e32 v191, s16
	v_mov_b32_e32 v156, v253
	v_cmp_gt_i32_e32 vcc, s41, v156
	v_add_u32_e32 v145, 0xffffc000, v156
	v_ashrrev_i32_e32 v157, 31, v156
	v_cndmask_b32_e32 v157, 0, v157, vcc
	v_cndmask_b32_e32 v156, v145, v156, vcc
	v_cndmask_b32_e32 v255, v226, v227, vcc
	v_cndmask_b32_e32 v254, v190, v191, vcc
	v_lshlrev_b64 v[156:157], 12, v[156:157]
	v_lshl_add_u64 v[156:157], v[254:255], 0, v[156:157]
	v_lshl_add_u64 v[156:157], v[156:157], 0, v[148:149]
	v_mov_b32_e32 v254, 0x8000
	v_mov_b32_e32 v255, 0
	v_lshl_add_u64 v[236:237], v[156:157], 0, v[254:255]
	v_add_u32_e32 v158, 0x10, v253
	v_cmp_gt_i32_e32 vcc, s41, v158
	v_add_u32_e32 v145, 0xffffc000, v158
	v_ashrrev_i32_e32 v159, 31, v158
	v_cndmask_b32_e32 v159, 0, v159, vcc
	v_cndmask_b32_e32 v158, v145, v158, vcc
	v_cndmask_b32_e32 v255, v226, v227, vcc
	v_cndmask_b32_e32 v254, v190, v191, vcc
	v_lshlrev_b64 v[158:159], 12, v[158:159]
	v_lshl_add_u64 v[158:159], v[254:255], 0, v[158:159]
	v_lshl_add_u64 v[158:159], v[158:159], 0, v[148:149]
	v_mov_b32_e32 v254, 0x8000
	v_mov_b32_e32 v255, 0
	v_lshl_add_u64 v[238:239], v[158:159], 0, v[254:255]
	v_add_u32_e32 v160, 0x20, v253
	v_cmp_gt_i32_e32 vcc, s41, v160
	v_add_u32_e32 v145, 0xffffc000, v160
	v_ashrrev_i32_e32 v161, 31, v160
	v_cndmask_b32_e32 v161, 0, v161, vcc
	v_cndmask_b32_e32 v160, v145, v160, vcc
	v_cndmask_b32_e32 v255, v226, v227, vcc
	v_cndmask_b32_e32 v254, v190, v191, vcc
	v_lshlrev_b64 v[160:161], 12, v[160:161]
	v_lshl_add_u64 v[160:161], v[254:255], 0, v[160:161]
	v_lshl_add_u64 v[160:161], v[160:161], 0, v[148:149]
	v_mov_b32_e32 v254, 0x8000
	v_mov_b32_e32 v255, 0
	v_lshl_add_u64 v[240:241], v[160:161], 0, v[254:255]
	v_add_u32_e32 v162, 0x30, v253
	v_cmp_gt_i32_e32 vcc, s41, v162
	v_add_u32_e32 v145, 0xffffc000, v162
	v_ashrrev_i32_e32 v163, 31, v162
	v_cndmask_b32_e32 v163, 0, v163, vcc
	v_cndmask_b32_e32 v162, v145, v162, vcc
	v_cndmask_b32_e32 v255, v226, v227, vcc
	v_cndmask_b32_e32 v254, v190, v191, vcc
	v_lshlrev_b64 v[162:163], 12, v[162:163]
	v_lshl_add_u64 v[162:163], v[254:255], 0, v[162:163]
	v_lshl_add_u64 v[162:163], v[162:163], 0, v[148:149]
	v_mov_b32_e32 v254, 0x8000
	v_mov_b32_e32 v255, 0
	v_lshl_add_u64 v[242:243], v[162:163], 0, v[254:255]
	v_add_u32_e32 v164, 0x80, v253
	v_cmp_gt_i32_e32 vcc, s41, v164
	v_add_u32_e32 v145, 0xffffc000, v164
	v_ashrrev_i32_e32 v165, 31, v164
	v_cndmask_b32_e32 v165, 0, v165, vcc
	v_cndmask_b32_e32 v164, v145, v164, vcc
	v_cndmask_b32_e32 v255, v226, v227, vcc
	v_cndmask_b32_e32 v254, v190, v191, vcc
	v_lshlrev_b64 v[164:165], 12, v[164:165]
	v_lshl_add_u64 v[164:165], v[254:255], 0, v[164:165]
	v_lshl_add_u64 v[164:165], v[164:165], 0, v[148:149]
	v_mov_b32_e32 v254, 0x8000
	v_mov_b32_e32 v255, 0
	v_lshl_add_u64 v[244:245], v[164:165], 0, v[254:255]
	v_add_u32_e32 v166, 0x90, v253
	v_cmp_gt_i32_e32 vcc, s41, v166
	v_add_u32_e32 v145, 0xffffc000, v166
	v_ashrrev_i32_e32 v167, 31, v166
	v_cndmask_b32_e32 v167, 0, v167, vcc
	v_cndmask_b32_e32 v166, v145, v166, vcc
	v_cndmask_b32_e32 v255, v226, v227, vcc
	v_cndmask_b32_e32 v254, v190, v191, vcc
	v_lshlrev_b64 v[166:167], 12, v[166:167]
	v_lshl_add_u64 v[166:167], v[254:255], 0, v[166:167]
	v_lshl_add_u64 v[166:167], v[166:167], 0, v[148:149]
	v_mov_b32_e32 v254, 0x8000
	v_mov_b32_e32 v255, 0
	v_lshl_add_u64 v[246:247], v[166:167], 0, v[254:255]
	v_add_u32_e32 v168, 0xa0, v253
	v_cmp_gt_i32_e32 vcc, s41, v168
	v_add_u32_e32 v145, 0xffffc000, v168
	v_ashrrev_i32_e32 v169, 31, v168
	v_cndmask_b32_e32 v169, 0, v169, vcc
	v_cndmask_b32_e32 v168, v145, v168, vcc
	v_cndmask_b32_e32 v255, v226, v227, vcc
	v_cndmask_b32_e32 v254, v190, v191, vcc
	v_lshlrev_b64 v[168:169], 12, v[168:169]
	v_lshl_add_u64 v[168:169], v[254:255], 0, v[168:169]
	v_lshl_add_u64 v[168:169], v[168:169], 0, v[148:149]
	v_mov_b32_e32 v254, 0x8000
	v_mov_b32_e32 v255, 0
	v_lshl_add_u64 v[248:249], v[168:169], 0, v[254:255]
	v_add_u32_e32 v170, 0xb0, v253
	v_cmp_gt_i32_e32 vcc, s41, v170
	v_add_u32_e32 v145, 0xffffc000, v170
	v_ashrrev_i32_e32 v171, 31, v170
	v_cndmask_b32_e32 v171, 0, v171, vcc
	v_cndmask_b32_e32 v170, v145, v170, vcc
	v_cndmask_b32_e32 v255, v226, v227, vcc
	v_cndmask_b32_e32 v254, v190, v191, vcc
	v_lshlrev_b64 v[170:171], 12, v[170:171]
	v_lshl_add_u64 v[170:171], v[254:255], 0, v[170:171]
	v_lshl_add_u64 v[170:171], v[170:171], 0, v[148:149]
	v_mov_b32_e32 v254, 0x8000
	v_mov_b32_e32 v255, 0
	v_lshl_add_u64 v[250:251], v[170:171], 0, v[254:255]
	global_load_dwordx4 v[172:175], v[156:157], off
	global_load_dwordx4 v[176:179], v[236:237], off
	global_load_dwordx4 v[182:185], v[156:157], off offset:512
	global_load_dwordx4 v[186:189], v[236:237], off offset:512
	global_load_dwordx4 v[194:197], v[158:159], off
	global_load_dwordx4 v[198:201], v[238:239], off
	global_load_dwordx4 v[202:205], v[158:159], off offset:512
	global_load_dwordx4 v[206:209], v[238:239], off offset:512
	global_load_dwordx4 v[210:213], v[160:161], off
	global_load_dwordx4 v[214:217], v[240:241], off
	global_load_dwordx4 v[218:221], v[160:161], off offset:512
	global_load_dwordx4 v[222:225], v[240:241], off offset:512
	global_load_dwordx4 v[228:231], v[162:163], off
	global_load_dwordx4 v[232:235], v[242:243], off
	v_mov_b32_e32 v254, v144
	v_ashrrev_i32_e32 v255, 31, v254
	v_lshlrev_b64 v[254:255], 11, v[254:255]
	v_lshl_add_u64 v[254:255], s[20:21], 0, v[254:255]
	v_lshl_add_u64 v[254:255], v[254:255], 0, v[146:147]
	s_waitcnt vmcnt(12)
; __device__ __forceinline__ unsigned cvt_pk_bf16(float lo, float hi) { unsigned r; asm volatile("v_cvt_pk_bf16_f32 %0, %1, %2" : "=v"(r) : "v"(lo), "v"(hi)); return r; }
;     __device__ __forceinline__ void operator()(const f32x4 (&acc)[2][2][4][2], const Unit& u, int wr, int wc, int fr, int fq) const {
; #pragma unroll
;         for (int ai = 0; ai < 2; ++ai)
; #pragma unroll
;             for (int m = 0; m < 4; ++m) {
;                 const int row = u.pm * BM + ai * HALF + wr * 64 + m * 16 + fr;
;                 const float* xr = xrow(xp, xs, row);
; #pragma unroll
;                 for (int bj = 0; bj < 2; ++bj) {
;                     const int col = u.pn * BM + bj * HALF + wc * 32 + 8 * fq;
;                     const f32x4 x0 = *(const f32x4*)(xr + col), x1v = *(const f32x4*)(xr + col + 4);
;                     const f32x4 v0 = acc[ai][bj][m][0] + x0, v1 = acc[ai][bj][m][1] + x1v;
;                     u32x4 w; w.x = cvt_pk_bf16(v0[0], v0[1]); w.y = cvt_pk_bf16(v0[2], v0[3]); w.z = cvt_pk_bf16(v1[0], v1[1]); w.w = cvt_pk_bf16(v1[2], v1[3]);
;                     *(u32x4*)(X1B + (size_t)row * D + col) = w;
;                 }
;             }
	v_add_f32_dpp v124, v172, v124 quad_perm:[0,1,2,3] row_mask:0xf bank_mask:0x3
	v_add_f32_dpp v124, v176, v124 row_ror:8 row_mask:0xf bank_mask:0xc
	v_add_f32_dpp v120, v172, v120 row_ror:8 row_mask:0xf bank_mask:0x3
	v_add_f32_dpp v120, v176, v120 quad_perm:[0,1,2,3] row_mask:0xf bank_mask:0xc
	v_add_f32_dpp v125, v173, v125 quad_perm:[0,1,2,3] row_mask:0xf bank_mask:0x3
	v_add_f32_dpp v125, v177, v125 row_ror:8 row_mask:0xf bank_mask:0xc
	v_add_f32_dpp v121, v173, v121 row_ror:8 row_mask:0xf bank_mask:0x3
	v_add_f32_dpp v121, v177, v121 quad_perm:[0,1,2,3] row_mask:0xf bank_mask:0xc
	v_add_f32_dpp v126, v174, v126 quad_perm:[0,1,2,3] row_mask:0xf bank_mask:0x3
	v_add_f32_dpp v126, v178, v126 row_ror:8 row_mask:0xf bank_mask:0xc
	v_add_f32_dpp v122, v174, v122 row_ror:8 row_mask:0xf bank_mask:0x3
	v_add_f32_dpp v122, v178, v122 quad_perm:[0,1,2,3] row_mask:0xf bank_mask:0xc
	v_add_f32_dpp v127, v175, v127 quad_perm:[0,1,2,3] row_mask:0xf bank_mask:0x3
	v_add_f32_dpp v127, v179, v127 row_ror:8 row_mask:0xf bank_mask:0xc
	v_add_f32_dpp v123, v175, v123 row_ror:8 row_mask:0xf bank_mask:0x3
	v_add_f32_dpp v123, v179, v123 quad_perm:[0,1,2,3] row_mask:0xf bank_mask:0xc
	v_cvt_pk_bf16_f32 v124, v124, v125
	v_cvt_pk_bf16_f32 v125, v126, v127
	v_cvt_pk_bf16_f32 v126, v120, v121
	v_cvt_pk_bf16_f32 v127, v122, v123
	s_nop 1
	global_store_dwordx4 v[254:255], v[124:127], off
	global_load_dwordx4 v[172:175], v[162:163], off offset:512
	global_load_dwordx4 v[176:179], v[242:243], off offset:512
	s_waitcnt vmcnt(13)
	v_add_f32_dpp v116, v182, v116 quad_perm:[0,1,2,3] row_mask:0xf bank_mask:0x3
	v_add_f32_dpp v116, v186, v116 row_ror:8 row_mask:0xf bank_mask:0xc
	v_add_f32_dpp v112, v182, v112 row_ror:8 row_mask:0xf bank_mask:0x3
	v_add_f32_dpp v112, v186, v112 quad_perm:[0,1,2,3] row_mask:0xf bank_mask:0xc
	v_add_f32_dpp v117, v183, v117 quad_perm:[0,1,2,3] row_mask:0xf bank_mask:0x3
	v_add_f32_dpp v117, v187, v117 row_ror:8 row_mask:0xf bank_mask:0xc
	v_add_f32_dpp v113, v183, v113 row_ror:8 row_mask:0xf bank_mask:0x3
	v_add_f32_dpp v113, v187, v113 quad_perm:[0,1,2,3] row_mask:0xf bank_mask:0xc
	v_add_f32_dpp v118, v184, v118 quad_perm:[0,1,2,3] row_mask:0xf bank_mask:0x3
	v_add_f32_dpp v118, v188, v118 row_ror:8 row_mask:0xf bank_mask:0xc
	v_add_f32_dpp v114, v184, v114 row_ror:8 row_mask:0xf bank_mask:0x3
	v_add_f32_dpp v114, v188, v114 quad_perm:[0,1,2,3] row_mask:0xf bank_mask:0xc
	v_add_f32_dpp v119, v185, v119 quad_perm:[0,1,2,3] row_mask:0xf bank_mask:0x3
	v_add_f32_dpp v119, v189, v119 row_ror:8 row_mask:0xf bank_mask:0xc
	v_add_f32_dpp v115, v185, v115 row_ror:8 row_mask:0xf bank_mask:0x3
	v_add_f32_dpp v115, v189, v115 quad_perm:[0,1,2,3] row_mask:0xf bank_mask:0xc
	v_cvt_pk_bf16_f32 v116, v116, v117
	v_cvt_pk_bf16_f32 v117, v118, v119
	v_cvt_pk_bf16_f32 v118, v112, v113
	v_cvt_pk_bf16_f32 v119, v114, v115
	s_nop 1
	global_store_dwordx4 v[254:255], v[116:119], off offset:256
	global_load_dwordx4 v[182:185], v[164:165], off
	global_load_dwordx4 v[186:189], v[244:245], off
	v_add_u32_e32 v254, 0x10, v144
	v_ashrrev_i32_e32 v255, 31, v254
	v_lshlrev_b64 v[254:255], 11, v[254:255]
	v_lshl_add_u64 v[254:255], s[20:21], 0, v[254:255]
	v_lshl_add_u64 v[254:255], v[254:255], 0, v[146:147]
	s_waitcnt vmcnt(14)
	v_add_f32_dpp v108, v194, v108 quad_perm:[0,1,2,3] row_mask:0xf bank_mask:0x3
	v_add_f32_dpp v108, v198, v108 row_ror:8 row_mask:0xf bank_mask:0xc
	v_add_f32_dpp v104, v194, v104 row_ror:8 row_mask:0xf bank_mask:0x3
	v_add_f32_dpp v104, v198, v104 quad_perm:[0,1,2,3] row_mask:0xf bank_mask:0xc
	v_add_f32_dpp v109, v195, v109 quad_perm:[0,1,2,3] row_mask:0xf bank_mask:0x3
	v_add_f32_dpp v109, v199, v109 row_ror:8 row_mask:0xf bank_mask:0xc
	v_add_f32_dpp v105, v195, v105 row_ror:8 row_mask:0xf bank_mask:0x3
	v_add_f32_dpp v105, v199, v105 quad_perm:[0,1,2,3] row_mask:0xf bank_mask:0xc
	v_add_f32_dpp v110, v196, v110 quad_perm:[0,1,2,3] row_mask:0xf bank_mask:0x3
	v_add_f32_dpp v110, v200, v110 row_ror:8 row_mask:0xf bank_mask:0xc
	v_add_f32_dpp v106, v196, v106 row_ror:8 row_mask:0xf bank_mask:0x3
	v_add_f32_dpp v106, v200, v106 quad_perm:[0,1,2,3] row_mask:0xf bank_mask:0xc
	v_add_f32_dpp v111, v197, v111 quad_perm:[0,1,2,3] row_mask:0xf bank_mask:0x3
	v_add_f32_dpp v111, v201, v111 row_ror:8 row_mask:0xf bank_mask:0xc
	v_add_f32_dpp v107, v197, v107 row_ror:8 row_mask:0xf bank_mask:0x3
	v_add_f32_dpp v107, v201, v107 quad_perm:[0,1,2,3] row_mask:0xf bank_mask:0xc
	v_cvt_pk_bf16_f32 v108, v108, v109
	v_cvt_pk_bf16_f32 v109, v110, v111
	v_cvt_pk_bf16_f32 v110, v104, v105
	v_cvt_pk_bf16_f32 v111, v106, v107
	s_nop 1
	global_store_dwordx4 v[254:255], v[108:111], off
	global_load_dwordx4 v[194:197], v[164:165], off offset:512
	global_load_dwordx4 v[198:201], v[244:245], off offset:512
	s_waitcnt vmcnt(15)
; __device__ __forceinline__ unsigned cvt_pk_bf16(float lo, float hi) { unsigned r; asm volatile("v_cvt_pk_bf16_f32 %0, %1, %2" : "=v"(r) : "v"(lo), "v"(hi)); return r; }
;     __device__ __forceinline__ void operator()(const f32x4 (&acc)[2][2][4][2], const Unit& u, int wr, int wc, int fr, int fq) const {
; #pragma unroll
;         for (int ai = 0; ai < 2; ++ai)
; #pragma unroll
;             for (int m = 0; m < 4; ++m) {
;                 const int row = u.pm * BM + ai * HALF + wr * 64 + m * 16 + fr;
;                 const float* xr = xrow(xp, xs, row);
; #pragma unroll
;                 for (int bj = 0; bj < 2; ++bj) {
;                     const int col = u.pn * BM + bj * HALF + wc * 32 + 8 * fq;
;                     const f32x4 x0 = *(const f32x4*)(xr + col), x1v = *(const f32x4*)(xr + col + 4);
;                     const f32x4 v0 = acc[ai][bj][m][0] + x0, v1 = acc[ai][bj][m][1] + x1v;
;                     u32x4 w; w.x = cvt_pk_bf16(v0[0], v0[1]); w.y = cvt_pk_bf16(v0[2], v0[3]); w.z = cvt_pk_bf16(v1[0], v1[1]); w.w = cvt_pk_bf16(v1[2], v1[3]);
;                     *(u32x4*)(X1B + (size_t)row * D + col) = w;
;                 }
;             }
	v_add_f32_dpp v100, v202, v100 quad_perm:[0,1,2,3] row_mask:0xf bank_mask:0x3
	v_add_f32_dpp v100, v206, v100 row_ror:8 row_mask:0xf bank_mask:0xc
	v_add_f32_dpp v96, v202, v96 row_ror:8 row_mask:0xf bank_mask:0x3
	v_add_f32_dpp v96, v206, v96 quad_perm:[0,1,2,3] row_mask:0xf bank_mask:0xc
	v_add_f32_dpp v101, v203, v101 quad_perm:[0,1,2,3] row_mask:0xf bank_mask:0x3
	v_add_f32_dpp v101, v207, v101 row_ror:8 row_mask:0xf bank_mask:0xc
	v_add_f32_dpp v97, v203, v97 row_ror:8 row_mask:0xf bank_mask:0x3
	v_add_f32_dpp v97, v207, v97 quad_perm:[0,1,2,3] row_mask:0xf bank_mask:0xc
	v_add_f32_dpp v102, v204, v102 quad_perm:[0,1,2,3] row_mask:0xf bank_mask:0x3
	v_add_f32_dpp v102, v208, v102 row_ror:8 row_mask:0xf bank_mask:0xc
	v_add_f32_dpp v98, v204, v98 row_ror:8 row_mask:0xf bank_mask:0x3
	v_add_f32_dpp v98, v208, v98 quad_perm:[0,1,2,3] row_mask:0xf bank_mask:0xc
	v_add_f32_dpp v103, v205, v103 quad_perm:[0,1,2,3] row_mask:0xf bank_mask:0x3
	v_add_f32_dpp v103, v209, v103 row_ror:8 row_mask:0xf bank_mask:0xc
	v_add_f32_dpp v99, v205, v99 row_ror:8 row_mask:0xf bank_mask:0x3
	v_add_f32_dpp v99, v209, v99 quad_perm:[0,1,2,3] row_mask:0xf bank_mask:0xc
	v_cvt_pk_bf16_f32 v100, v100, v101
	v_cvt_pk_bf16_f32 v101, v102, v103
	v_cvt_pk_bf16_f32 v102, v96, v97
	v_cvt_pk_bf16_f32 v103, v98, v99
	s_nop 1
	global_store_dwordx4 v[254:255], v[100:103], off offset:256
	global_load_dwordx4 v[202:205], v[166:167], off
	global_load_dwordx4 v[206:209], v[246:247], off
	v_add_u32_e32 v254, 0x20, v144
	v_ashrrev_i32_e32 v255, 31, v254
	v_lshlrev_b64 v[254:255], 11, v[254:255]
	v_lshl_add_u64 v[254:255], s[20:21], 0, v[254:255]
	v_lshl_add_u64 v[254:255], v[254:255], 0, v[146:147]
	s_waitcnt vmcnt(16)
	v_add_f32_dpp v92, v210, v92 quad_perm:[0,1,2,3] row_mask:0xf bank_mask:0x3
	v_add_f32_dpp v92, v214, v92 row_ror:8 row_mask:0xf bank_mask:0xc
	v_add_f32_dpp v88, v210, v88 row_ror:8 row_mask:0xf bank_mask:0x3
	v_add_f32_dpp v88, v214, v88 quad_perm:[0,1,2,3] row_mask:0xf bank_mask:0xc
	v_add_f32_dpp v93, v211, v93 quad_perm:[0,1,2,3] row_mask:0xf bank_mask:0x3
	v_add_f32_dpp v93, v215, v93 row_ror:8 row_mask:0xf bank_mask:0xc
	v_add_f32_dpp v89, v211, v89 row_ror:8 row_mask:0xf bank_mask:0x3
	v_add_f32_dpp v89, v215, v89 quad_perm:[0,1,2,3] row_mask:0xf bank_mask:0xc
	v_add_f32_dpp v94, v212, v94 quad_perm:[0,1,2,3] row_mask:0xf bank_mask:0x3
	v_add_f32_dpp v94, v216, v94 row_ror:8 row_mask:0xf bank_mask:0xc
	v_add_f32_dpp v90, v212, v90 row_ror:8 row_mask:0xf bank_mask:0x3
	v_add_f32_dpp v90, v216, v90 quad_perm:[0,1,2,3] row_mask:0xf bank_mask:0xc
	v_add_f32_dpp v95, v213, v95 quad_perm:[0,1,2,3] row_mask:0xf bank_mask:0x3
	v_add_f32_dpp v95, v217, v95 row_ror:8 row_mask:0xf bank_mask:0xc
	v_add_f32_dpp v91, v213, v91 row_ror:8 row_mask:0xf bank_mask:0x3
	v_add_f32_dpp v91, v217, v91 quad_perm:[0,1,2,3] row_mask:0xf bank_mask:0xc
	v_cvt_pk_bf16_f32 v92, v92, v93
	v_cvt_pk_bf16_f32 v93, v94, v95
	v_cvt_pk_bf16_f32 v94, v88, v89
	v_cvt_pk_bf16_f32 v95, v90, v91
	s_nop 1
	global_store_dwordx4 v[254:255], v[92:95], off
	global_load_dwordx4 v[210:213], v[166:167], off offset:512
	global_load_dwordx4 v[214:217], v[246:247], off offset:512
	s_waitcnt vmcnt(17)
	v_add_f32_dpp v84, v218, v84 quad_perm:[0,1,2,3] row_mask:0xf bank_mask:0x3
	v_add_f32_dpp v84, v222, v84 row_ror:8 row_mask:0xf bank_mask:0xc
	v_add_f32_dpp v80, v218, v80 row_ror:8 row_mask:0xf bank_mask:0x3
	v_add_f32_dpp v80, v222, v80 quad_perm:[0,1,2,3] row_mask:0xf bank_mask:0xc
	v_add_f32_dpp v85, v219, v85 quad_perm:[0,1,2,3] row_mask:0xf bank_mask:0x3
	v_add_f32_dpp v85, v223, v85 row_ror:8 row_mask:0xf bank_mask:0xc
	v_add_f32_dpp v81, v219, v81 row_ror:8 row_mask:0xf bank_mask:0x3
	v_add_f32_dpp v81, v223, v81 quad_perm:[0,1,2,3] row_mask:0xf bank_mask:0xc
	v_add_f32_dpp v86, v220, v86 quad_perm:[0,1,2,3] row_mask:0xf bank_mask:0x3
	v_add_f32_dpp v86, v224, v86 row_ror:8 row_mask:0xf bank_mask:0xc
	v_add_f32_dpp v82, v220, v82 row_ror:8 row_mask:0xf bank_mask:0x3
	v_add_f32_dpp v82, v224, v82 quad_perm:[0,1,2,3] row_mask:0xf bank_mask:0xc
	v_add_f32_dpp v87, v221, v87 quad_perm:[0,1,2,3] row_mask:0xf bank_mask:0x3
	v_add_f32_dpp v87, v225, v87 row_ror:8 row_mask:0xf bank_mask:0xc
	v_add_f32_dpp v83, v221, v83 row_ror:8 row_mask:0xf bank_mask:0x3
	v_add_f32_dpp v83, v225, v83 quad_perm:[0,1,2,3] row_mask:0xf bank_mask:0xc
	v_cvt_pk_bf16_f32 v84, v84, v85
	v_cvt_pk_bf16_f32 v85, v86, v87
	v_cvt_pk_bf16_f32 v86, v80, v81
	v_cvt_pk_bf16_f32 v87, v82, v83
	s_nop 1
	global_store_dwordx4 v[254:255], v[84:87], off offset:256
	global_load_dwordx4 v[218:221], v[168:169], off
	global_load_dwordx4 v[222:225], v[248:249], off
	v_add_u32_e32 v254, 0x30, v144
	v_ashrrev_i32_e32 v255, 31, v254
	v_lshlrev_b64 v[254:255], 11, v[254:255]
	v_lshl_add_u64 v[254:255], s[20:21], 0, v[254:255]
	v_lshl_add_u64 v[254:255], v[254:255], 0, v[146:147]
	s_waitcnt vmcnt(18)
	v_add_f32_dpp v76, v228, v76 quad_perm:[0,1,2,3] row_mask:0xf bank_mask:0x3
	v_add_f32_dpp v76, v232, v76 row_ror:8 row_mask:0xf bank_mask:0xc
	v_add_f32_dpp v72, v228, v72 row_ror:8 row_mask:0xf bank_mask:0x3
	v_add_f32_dpp v72, v232, v72 quad_perm:[0,1,2,3] row_mask:0xf bank_mask:0xc
	v_add_f32_dpp v77, v229, v77 quad_perm:[0,1,2,3] row_mask:0xf bank_mask:0x3
	v_add_f32_dpp v77, v233, v77 row_ror:8 row_mask:0xf bank_mask:0xc
	v_add_f32_dpp v73, v229, v73 row_ror:8 row_mask:0xf bank_mask:0x3
	v_add_f32_dpp v73, v233, v73 quad_perm:[0,1,2,3] row_mask:0xf bank_mask:0xc
	v_add_f32_dpp v78, v230, v78 quad_perm:[0,1,2,3] row_mask:0xf bank_mask:0x3
	v_add_f32_dpp v78, v234, v78 row_ror:8 row_mask:0xf bank_mask:0xc
	v_add_f32_dpp v74, v230, v74 row_ror:8 row_mask:0xf bank_mask:0x3
	v_add_f32_dpp v74, v234, v74 quad_perm:[0,1,2,3] row_mask:0xf bank_mask:0xc
	v_add_f32_dpp v79, v231, v79 quad_perm:[0,1,2,3] row_mask:0xf bank_mask:0x3
	v_add_f32_dpp v79, v235, v79 row_ror:8 row_mask:0xf bank_mask:0xc
	v_add_f32_dpp v75, v231, v75 row_ror:8 row_mask:0xf bank_mask:0x3
	v_add_f32_dpp v75, v235, v75 quad_perm:[0,1,2,3] row_mask:0xf bank_mask:0xc
	v_cvt_pk_bf16_f32 v76, v76, v77
	v_cvt_pk_bf16_f32 v77, v78, v79
	v_cvt_pk_bf16_f32 v78, v72, v73
	v_cvt_pk_bf16_f32 v79, v74, v75
	s_nop 1
	global_store_dwordx4 v[254:255], v[76:79], off
	global_load_dwordx4 v[228:231], v[168:169], off offset:512
	global_load_dwordx4 v[232:235], v[248:249], off offset:512
	s_waitcnt vmcnt(18)
; __device__ __forceinline__ unsigned cvt_pk_bf16(float lo, float hi) { unsigned r; asm volatile("v_cvt_pk_bf16_f32 %0, %1, %2" : "=v"(r) : "v"(lo), "v"(hi)); return r; }
;     __device__ __forceinline__ void operator()(const f32x4 (&acc)[2][2][4][2], const Unit& u, int wr, int wc, int fr, int fq) const {
; #pragma unroll
;         for (int ai = 0; ai < 2; ++ai)
; #pragma unroll
;             for (int m = 0; m < 4; ++m) {
;                 const int row = u.pm * BM + ai * HALF + wr * 64 + m * 16 + fr;
;                 const float* xr = xrow(xp, xs, row);
; #pragma unroll
;                 for (int bj = 0; bj < 2; ++bj) {
;                     const int col = u.pn * BM + bj * HALF + wc * 32 + 8 * fq;
;                     const f32x4 x0 = *(const f32x4*)(xr + col), x1v = *(const f32x4*)(xr + col + 4);
;                     const f32x4 v0 = acc[ai][bj][m][0] + x0, v1 = acc[ai][bj][m][1] + x1v;
;                     u32x4 w; w.x = cvt_pk_bf16(v0[0], v0[1]); w.y = cvt_pk_bf16(v0[2], v0[3]); w.z = cvt_pk_bf16(v1[0], v1[1]); w.w = cvt_pk_bf16(v1[2], v1[3]);
;                     *(u32x4*)(X1B + (size_t)row * D + col) = w;
;                 }
;             }
	v_add_f32_dpp v68, v172, v68 quad_perm:[0,1,2,3] row_mask:0xf bank_mask:0x3
	v_add_f32_dpp v68, v176, v68 row_ror:8 row_mask:0xf bank_mask:0xc
	v_add_f32_dpp v64, v172, v64 row_ror:8 row_mask:0xf bank_mask:0x3
	v_add_f32_dpp v64, v176, v64 quad_perm:[0,1,2,3] row_mask:0xf bank_mask:0xc
	v_add_f32_dpp v69, v173, v69 quad_perm:[0,1,2,3] row_mask:0xf bank_mask:0x3
	v_add_f32_dpp v69, v177, v69 row_ror:8 row_mask:0xf bank_mask:0xc
	v_add_f32_dpp v65, v173, v65 row_ror:8 row_mask:0xf bank_mask:0x3
	v_add_f32_dpp v65, v177, v65 quad_perm:[0,1,2,3] row_mask:0xf bank_mask:0xc
	v_add_f32_dpp v70, v174, v70 quad_perm:[0,1,2,3] row_mask:0xf bank_mask:0x3
	v_add_f32_dpp v70, v178, v70 row_ror:8 row_mask:0xf bank_mask:0xc
	v_add_f32_dpp v66, v174, v66 row_ror:8 row_mask:0xf bank_mask:0x3
	v_add_f32_dpp v66, v178, v66 quad_perm:[0,1,2,3] row_mask:0xf bank_mask:0xc
	v_add_f32_dpp v71, v175, v71 quad_perm:[0,1,2,3] row_mask:0xf bank_mask:0x3
	v_add_f32_dpp v71, v179, v71 row_ror:8 row_mask:0xf bank_mask:0xc
	v_add_f32_dpp v67, v175, v67 row_ror:8 row_mask:0xf bank_mask:0x3
	v_add_f32_dpp v67, v179, v67 quad_perm:[0,1,2,3] row_mask:0xf bank_mask:0xc
	v_cvt_pk_bf16_f32 v68, v68, v69
	v_cvt_pk_bf16_f32 v69, v70, v71
	v_cvt_pk_bf16_f32 v70, v64, v65
	v_cvt_pk_bf16_f32 v71, v66, v67
	s_nop 1
	global_store_dwordx4 v[254:255], v[68:71], off offset:256
	global_load_dwordx4 v[172:175], v[170:171], off
	global_load_dwordx4 v[176:179], v[250:251], off
	v_add_u32_e32 v254, 0x80, v144
	v_ashrrev_i32_e32 v255, 31, v254
	v_lshlrev_b64 v[254:255], 11, v[254:255]
	v_lshl_add_u64 v[254:255], s[20:21], 0, v[254:255]
	v_lshl_add_u64 v[254:255], v[254:255], 0, v[146:147]
	s_waitcnt vmcnt(18)
	v_add_f32_dpp v60, v182, v60 quad_perm:[0,1,2,3] row_mask:0xf bank_mask:0x3
	v_add_f32_dpp v60, v186, v60 row_ror:8 row_mask:0xf bank_mask:0xc
	v_add_f32_dpp v56, v182, v56 row_ror:8 row_mask:0xf bank_mask:0x3
	v_add_f32_dpp v56, v186, v56 quad_perm:[0,1,2,3] row_mask:0xf bank_mask:0xc
	v_add_f32_dpp v61, v183, v61 quad_perm:[0,1,2,3] row_mask:0xf bank_mask:0x3
	v_add_f32_dpp v61, v187, v61 row_ror:8 row_mask:0xf bank_mask:0xc
	v_add_f32_dpp v57, v183, v57 row_ror:8 row_mask:0xf bank_mask:0x3
	v_add_f32_dpp v57, v187, v57 quad_perm:[0,1,2,3] row_mask:0xf bank_mask:0xc
	v_add_f32_dpp v62, v184, v62 quad_perm:[0,1,2,3] row_mask:0xf bank_mask:0x3
	v_add_f32_dpp v62, v188, v62 row_ror:8 row_mask:0xf bank_mask:0xc
	v_add_f32_dpp v58, v184, v58 row_ror:8 row_mask:0xf bank_mask:0x3
	v_add_f32_dpp v58, v188, v58 quad_perm:[0,1,2,3] row_mask:0xf bank_mask:0xc
	v_add_f32_dpp v63, v185, v63 quad_perm:[0,1,2,3] row_mask:0xf bank_mask:0x3
	v_add_f32_dpp v63, v189, v63 row_ror:8 row_mask:0xf bank_mask:0xc
	v_add_f32_dpp v59, v185, v59 row_ror:8 row_mask:0xf bank_mask:0x3
	v_add_f32_dpp v59, v189, v59 quad_perm:[0,1,2,3] row_mask:0xf bank_mask:0xc
	v_cvt_pk_bf16_f32 v60, v60, v61
	v_cvt_pk_bf16_f32 v61, v62, v63
	v_cvt_pk_bf16_f32 v62, v56, v57
	v_cvt_pk_bf16_f32 v63, v58, v59
	s_nop 1
	global_store_dwordx4 v[254:255], v[60:63], off
	global_load_dwordx4 v[182:185], v[170:171], off offset:512
	global_load_dwordx4 v[186:189], v[250:251], off offset:512
	s_waitcnt vmcnt(18)
	v_add_f32_dpp v52, v194, v52 quad_perm:[0,1,2,3] row_mask:0xf bank_mask:0x3
	v_add_f32_dpp v52, v198, v52 row_ror:8 row_mask:0xf bank_mask:0xc
	v_add_f32_dpp v48, v194, v48 row_ror:8 row_mask:0xf bank_mask:0x3
	v_add_f32_dpp v48, v198, v48 quad_perm:[0,1,2,3] row_mask:0xf bank_mask:0xc
	v_add_f32_dpp v53, v195, v53 quad_perm:[0,1,2,3] row_mask:0xf bank_mask:0x3
	v_add_f32_dpp v53, v199, v53 row_ror:8 row_mask:0xf bank_mask:0xc
	v_add_f32_dpp v49, v195, v49 row_ror:8 row_mask:0xf bank_mask:0x3
	v_add_f32_dpp v49, v199, v49 quad_perm:[0,1,2,3] row_mask:0xf bank_mask:0xc
	v_add_f32_dpp v54, v196, v54 quad_perm:[0,1,2,3] row_mask:0xf bank_mask:0x3
	v_add_f32_dpp v54, v200, v54 row_ror:8 row_mask:0xf bank_mask:0xc
	v_add_f32_dpp v50, v196, v50 row_ror:8 row_mask:0xf bank_mask:0x3
	v_add_f32_dpp v50, v200, v50 quad_perm:[0,1,2,3] row_mask:0xf bank_mask:0xc
	v_add_f32_dpp v55, v197, v55 quad_perm:[0,1,2,3] row_mask:0xf bank_mask:0x3
	v_add_f32_dpp v55, v201, v55 row_ror:8 row_mask:0xf bank_mask:0xc
	v_add_f32_dpp v51, v197, v51 row_ror:8 row_mask:0xf bank_mask:0x3
	v_add_f32_dpp v51, v201, v51 quad_perm:[0,1,2,3] row_mask:0xf bank_mask:0xc
	v_cvt_pk_bf16_f32 v52, v52, v53
	v_cvt_pk_bf16_f32 v53, v54, v55
	v_cvt_pk_bf16_f32 v54, v48, v49
	v_cvt_pk_bf16_f32 v55, v50, v51
	s_nop 1
	global_store_dwordx4 v[254:255], v[52:55], off offset:256
	v_add_u32_e32 v254, 0x90, v144
	v_ashrrev_i32_e32 v255, 31, v254
	v_lshlrev_b64 v[254:255], 11, v[254:255]
	v_lshl_add_u64 v[254:255], s[20:21], 0, v[254:255]
	v_lshl_add_u64 v[254:255], v[254:255], 0, v[146:147]
	s_waitcnt vmcnt(16)
	v_add_f32_dpp v44, v202, v44 quad_perm:[0,1,2,3] row_mask:0xf bank_mask:0x3
	v_add_f32_dpp v44, v206, v44 row_ror:8 row_mask:0xf bank_mask:0xc
	v_add_f32_dpp v40, v202, v40 row_ror:8 row_mask:0xf bank_mask:0x3
	v_add_f32_dpp v40, v206, v40 quad_perm:[0,1,2,3] row_mask:0xf bank_mask:0xc
	v_add_f32_dpp v45, v203, v45 quad_perm:[0,1,2,3] row_mask:0xf bank_mask:0x3
	v_add_f32_dpp v45, v207, v45 row_ror:8 row_mask:0xf bank_mask:0xc
	v_add_f32_dpp v41, v203, v41 row_ror:8 row_mask:0xf bank_mask:0x3
	v_add_f32_dpp v41, v207, v41 quad_perm:[0,1,2,3] row_mask:0xf bank_mask:0xc
	v_add_f32_dpp v46, v204, v46 quad_perm:[0,1,2,3] row_mask:0xf bank_mask:0x3
	v_add_f32_dpp v46, v208, v46 row_ror:8 row_mask:0xf bank_mask:0xc
	v_add_f32_dpp v42, v204, v42 row_ror:8 row_mask:0xf bank_mask:0x3
	v_add_f32_dpp v42, v208, v42 quad_perm:[0,1,2,3] row_mask:0xf bank_mask:0xc
	v_add_f32_dpp v47, v205, v47 quad_perm:[0,1,2,3] row_mask:0xf bank_mask:0x3
	v_add_f32_dpp v47, v209, v47 row_ror:8 row_mask:0xf bank_mask:0xc
	v_add_f32_dpp v43, v205, v43 row_ror:8 row_mask:0xf bank_mask:0x3
	v_add_f32_dpp v43, v209, v43 quad_perm:[0,1,2,3] row_mask:0xf bank_mask:0xc
	v_cvt_pk_bf16_f32 v44, v44, v45
	v_cvt_pk_bf16_f32 v45, v46, v47
	v_cvt_pk_bf16_f32 v46, v40, v41
	v_cvt_pk_bf16_f32 v47, v42, v43
	s_nop 1
	global_store_dwordx4 v[254:255], v[44:47], off
	s_waitcnt vmcnt(14)
; __device__ __forceinline__ unsigned cvt_pk_bf16(float lo, float hi) { unsigned r; asm volatile("v_cvt_pk_bf16_f32 %0, %1, %2" : "=v"(r) : "v"(lo), "v"(hi)); return r; }
;     __device__ __forceinline__ void operator()(const f32x4 (&acc)[2][2][4][2], const Unit& u, int wr, int wc, int fr, int fq) const {
; #pragma unroll
;         for (int ai = 0; ai < 2; ++ai)
; #pragma unroll
;             for (int m = 0; m < 4; ++m) {
;                 const int row = u.pm * BM + ai * HALF + wr * 64 + m * 16 + fr;
;                 const float* xr = xrow(xp, xs, row);
; #pragma unroll
;                 for (int bj = 0; bj < 2; ++bj) {
;                     const int col = u.pn * BM + bj * HALF + wc * 32 + 8 * fq;
;                     const f32x4 x0 = *(const f32x4*)(xr + col), x1v = *(const f32x4*)(xr + col + 4);
;                     const f32x4 v0 = acc[ai][bj][m][0] + x0, v1 = acc[ai][bj][m][1] + x1v;
;                     u32x4 w; w.x = cvt_pk_bf16(v0[0], v0[1]); w.y = cvt_pk_bf16(v0[2], v0[3]); w.z = cvt_pk_bf16(v1[0], v1[1]); w.w = cvt_pk_bf16(v1[2], v1[3]);
;                     *(u32x4*)(X1B + (size_t)row * D + col) = w;
;                 }
;             }
	v_add_f32_dpp v36, v210, v36 quad_perm:[0,1,2,3] row_mask:0xf bank_mask:0x3
	v_add_f32_dpp v36, v214, v36 row_ror:8 row_mask:0xf bank_mask:0xc
	v_add_f32_dpp v32, v210, v32 row_ror:8 row_mask:0xf bank_mask:0x3
	v_add_f32_dpp v32, v214, v32 quad_perm:[0,1,2,3] row_mask:0xf bank_mask:0xc
	v_add_f32_dpp v37, v211, v37 quad_perm:[0,1,2,3] row_mask:0xf bank_mask:0x3
	v_add_f32_dpp v37, v215, v37 row_ror:8 row_mask:0xf bank_mask:0xc
	v_add_f32_dpp v33, v211, v33 row_ror:8 row_mask:0xf bank_mask:0x3
	v_add_f32_dpp v33, v215, v33 quad_perm:[0,1,2,3] row_mask:0xf bank_mask:0xc
	v_add_f32_dpp v38, v212, v38 quad_perm:[0,1,2,3] row_mask:0xf bank_mask:0x3
	v_add_f32_dpp v38, v216, v38 row_ror:8 row_mask:0xf bank_mask:0xc
	v_add_f32_dpp v34, v212, v34 row_ror:8 row_mask:0xf bank_mask:0x3
	v_add_f32_dpp v34, v216, v34 quad_perm:[0,1,2,3] row_mask:0xf bank_mask:0xc
	v_add_f32_dpp v39, v213, v39 quad_perm:[0,1,2,3] row_mask:0xf bank_mask:0x3
	v_add_f32_dpp v39, v217, v39 row_ror:8 row_mask:0xf bank_mask:0xc
	v_add_f32_dpp v35, v213, v35 row_ror:8 row_mask:0xf bank_mask:0x3
	v_add_f32_dpp v35, v217, v35 quad_perm:[0,1,2,3] row_mask:0xf bank_mask:0xc
	v_cvt_pk_bf16_f32 v36, v36, v37
	v_cvt_pk_bf16_f32 v37, v38, v39
	v_cvt_pk_bf16_f32 v38, v32, v33
	v_cvt_pk_bf16_f32 v39, v34, v35
	s_nop 1
	global_store_dwordx4 v[254:255], v[36:39], off offset:256
	v_add_u32_e32 v254, 0xa0, v144
	v_ashrrev_i32_e32 v255, 31, v254
	v_lshlrev_b64 v[254:255], 11, v[254:255]
	v_lshl_add_u64 v[254:255], s[20:21], 0, v[254:255]
	v_lshl_add_u64 v[254:255], v[254:255], 0, v[146:147]
	s_waitcnt vmcnt(12)
	v_add_f32_dpp v28, v218, v28 quad_perm:[0,1,2,3] row_mask:0xf bank_mask:0x3
	v_add_f32_dpp v28, v222, v28 row_ror:8 row_mask:0xf bank_mask:0xc
	v_add_f32_dpp v24, v218, v24 row_ror:8 row_mask:0xf bank_mask:0x3
	v_add_f32_dpp v24, v222, v24 quad_perm:[0,1,2,3] row_mask:0xf bank_mask:0xc
	v_add_f32_dpp v29, v219, v29 quad_perm:[0,1,2,3] row_mask:0xf bank_mask:0x3
	v_add_f32_dpp v29, v223, v29 row_ror:8 row_mask:0xf bank_mask:0xc
	v_add_f32_dpp v25, v219, v25 row_ror:8 row_mask:0xf bank_mask:0x3
	v_add_f32_dpp v25, v223, v25 quad_perm:[0,1,2,3] row_mask:0xf bank_mask:0xc
	v_add_f32_dpp v30, v220, v30 quad_perm:[0,1,2,3] row_mask:0xf bank_mask:0x3
	v_add_f32_dpp v30, v224, v30 row_ror:8 row_mask:0xf bank_mask:0xc
	v_add_f32_dpp v26, v220, v26 row_ror:8 row_mask:0xf bank_mask:0x3
	v_add_f32_dpp v26, v224, v26 quad_perm:[0,1,2,3] row_mask:0xf bank_mask:0xc
	v_add_f32_dpp v31, v221, v31 quad_perm:[0,1,2,3] row_mask:0xf bank_mask:0x3
	v_add_f32_dpp v31, v225, v31 row_ror:8 row_mask:0xf bank_mask:0xc
	v_add_f32_dpp v27, v221, v27 row_ror:8 row_mask:0xf bank_mask:0x3
	v_add_f32_dpp v27, v225, v27 quad_perm:[0,1,2,3] row_mask:0xf bank_mask:0xc
	v_cvt_pk_bf16_f32 v28, v28, v29
	v_cvt_pk_bf16_f32 v29, v30, v31
	v_cvt_pk_bf16_f32 v30, v24, v25
	v_cvt_pk_bf16_f32 v31, v26, v27
	s_nop 1
	global_store_dwordx4 v[254:255], v[28:31], off
	s_waitcnt vmcnt(10)
; __device__ __forceinline__ unsigned cvt_pk_bf16(float lo, float hi) { unsigned r; asm volatile("v_cvt_pk_bf16_f32 %0, %1, %2" : "=v"(r) : "v"(lo), "v"(hi)); return r; }
;     __device__ __forceinline__ void operator()(const f32x4 (&acc)[2][2][4][2], const Unit& u, int wr, int wc, int fr, int fq) const {
; #pragma unroll
;         for (int ai = 0; ai < 2; ++ai)
; #pragma unroll
;             for (int m = 0; m < 4; ++m) {
;                 const int row = u.pm * BM + ai * HALF + wr * 64 + m * 16 + fr;
;                 const float* xr = xrow(xp, xs, row);
; #pragma unroll
;                 for (int bj = 0; bj < 2; ++bj) {
;                     const int col = u.pn * BM + bj * HALF + wc * 32 + 8 * fq;
;                     const f32x4 x0 = *(const f32x4*)(xr + col), x1v = *(const f32x4*)(xr + col + 4);
;                     const f32x4 v0 = acc[ai][bj][m][0] + x0, v1 = acc[ai][bj][m][1] + x1v;
;                     u32x4 w; w.x = cvt_pk_bf16(v0[0], v0[1]); w.y = cvt_pk_bf16(v0[2], v0[3]); w.z = cvt_pk_bf16(v1[0], v1[1]); w.w = cvt_pk_bf16(v1[2], v1[3]);
;                     *(u32x4*)(X1B + (size_t)row * D + col) = w;
;                 }
;             }
	v_add_f32_dpp v20, v228, v20 quad_perm:[0,1,2,3] row_mask:0xf bank_mask:0x3
	v_add_f32_dpp v20, v232, v20 row_ror:8 row_mask:0xf bank_mask:0xc
	v_add_f32_dpp v16, v228, v16 row_ror:8 row_mask:0xf bank_mask:0x3
	v_add_f32_dpp v16, v232, v16 quad_perm:[0,1,2,3] row_mask:0xf bank_mask:0xc
	v_add_f32_dpp v21, v229, v21 quad_perm:[0,1,2,3] row_mask:0xf bank_mask:0x3
	v_add_f32_dpp v21, v233, v21 row_ror:8 row_mask:0xf bank_mask:0xc
	v_add_f32_dpp v17, v229, v17 row_ror:8 row_mask:0xf bank_mask:0x3
	v_add_f32_dpp v17, v233, v17 quad_perm:[0,1,2,3] row_mask:0xf bank_mask:0xc
	v_add_f32_dpp v22, v230, v22 quad_perm:[0,1,2,3] row_mask:0xf bank_mask:0x3
	v_add_f32_dpp v22, v234, v22 row_ror:8 row_mask:0xf bank_mask:0xc
	v_add_f32_dpp v18, v230, v18 row_ror:8 row_mask:0xf bank_mask:0x3
	v_add_f32_dpp v18, v234, v18 quad_perm:[0,1,2,3] row_mask:0xf bank_mask:0xc
	v_add_f32_dpp v23, v231, v23 quad_perm:[0,1,2,3] row_mask:0xf bank_mask:0x3
	v_add_f32_dpp v23, v235, v23 row_ror:8 row_mask:0xf bank_mask:0xc
	v_add_f32_dpp v19, v231, v19 row_ror:8 row_mask:0xf bank_mask:0x3
	v_add_f32_dpp v19, v235, v19 quad_perm:[0,1,2,3] row_mask:0xf bank_mask:0xc
	v_cvt_pk_bf16_f32 v20, v20, v21
	v_cvt_pk_bf16_f32 v21, v22, v23
	v_cvt_pk_bf16_f32 v22, v16, v17
	v_cvt_pk_bf16_f32 v23, v18, v19
	s_nop 1
	global_store_dwordx4 v[254:255], v[20:23], off offset:256
	v_add_u32_e32 v254, 0xb0, v144
	v_ashrrev_i32_e32 v255, 31, v254
	v_lshlrev_b64 v[254:255], 11, v[254:255]
	v_lshl_add_u64 v[254:255], s[20:21], 0, v[254:255]
	v_lshl_add_u64 v[254:255], v[254:255], 0, v[146:147]
	s_waitcnt vmcnt(8)
	v_add_f32_dpp v12, v172, v12 quad_perm:[0,1,2,3] row_mask:0xf bank_mask:0x3
	v_add_f32_dpp v12, v176, v12 row_ror:8 row_mask:0xf bank_mask:0xc
	v_add_f32_dpp v8, v172, v8 row_ror:8 row_mask:0xf bank_mask:0x3
	v_add_f32_dpp v8, v176, v8 quad_perm:[0,1,2,3] row_mask:0xf bank_mask:0xc
	v_add_f32_dpp v13, v173, v13 quad_perm:[0,1,2,3] row_mask:0xf bank_mask:0x3
	v_add_f32_dpp v13, v177, v13 row_ror:8 row_mask:0xf bank_mask:0xc
	v_add_f32_dpp v9, v173, v9 row_ror:8 row_mask:0xf bank_mask:0x3
	v_add_f32_dpp v9, v177, v9 quad_perm:[0,1,2,3] row_mask:0xf bank_mask:0xc
	v_add_f32_dpp v14, v174, v14 quad_perm:[0,1,2,3] row_mask:0xf bank_mask:0x3
	v_add_f32_dpp v14, v178, v14 row_ror:8 row_mask:0xf bank_mask:0xc
	v_add_f32_dpp v10, v174, v10 row_ror:8 row_mask:0xf bank_mask:0x3
	v_add_f32_dpp v10, v178, v10 quad_perm:[0,1,2,3] row_mask:0xf bank_mask:0xc
	v_add_f32_dpp v15, v175, v15 quad_perm:[0,1,2,3] row_mask:0xf bank_mask:0x3
	v_add_f32_dpp v15, v179, v15 row_ror:8 row_mask:0xf bank_mask:0xc
	v_add_f32_dpp v11, v175, v11 row_ror:8 row_mask:0xf bank_mask:0x3
	v_add_f32_dpp v11, v179, v11 quad_perm:[0,1,2,3] row_mask:0xf bank_mask:0xc
	v_cvt_pk_bf16_f32 v12, v12, v13
	v_cvt_pk_bf16_f32 v13, v14, v15
	v_cvt_pk_bf16_f32 v14, v8, v9
	v_cvt_pk_bf16_f32 v15, v10, v11
	s_nop 1
	global_store_dwordx4 v[254:255], v[12:15], off
	s_waitcnt vmcnt(6)
	v_add_f32_dpp v4, v182, v4 quad_perm:[0,1,2,3] row_mask:0xf bank_mask:0x3
	v_add_f32_dpp v4, v186, v4 row_ror:8 row_mask:0xf bank_mask:0xc
	v_add_f32_dpp v0, v182, v0 row_ror:8 row_mask:0xf bank_mask:0x3
	v_add_f32_dpp v0, v186, v0 quad_perm:[0,1,2,3] row_mask:0xf bank_mask:0xc
	v_add_f32_dpp v5, v183, v5 quad_perm:[0,1,2,3] row_mask:0xf bank_mask:0x3
	v_add_f32_dpp v5, v187, v5 row_ror:8 row_mask:0xf bank_mask:0xc
	v_add_f32_dpp v1, v183, v1 row_ror:8 row_mask:0xf bank_mask:0x3
	v_add_f32_dpp v1, v187, v1 quad_perm:[0,1,2,3] row_mask:0xf bank_mask:0xc
	v_add_f32_dpp v6, v184, v6 quad_perm:[0,1,2,3] row_mask:0xf bank_mask:0x3
	v_add_f32_dpp v6, v188, v6 row_ror:8 row_mask:0xf bank_mask:0xc
	v_add_f32_dpp v2, v184, v2 row_ror:8 row_mask:0xf bank_mask:0x3
	v_add_f32_dpp v2, v188, v2 quad_perm:[0,1,2,3] row_mask:0xf bank_mask:0xc
	v_add_f32_dpp v7, v185, v7 quad_perm:[0,1,2,3] row_mask:0xf bank_mask:0x3
	v_add_f32_dpp v7, v189, v7 row_ror:8 row_mask:0xf bank_mask:0xc
	v_add_f32_dpp v3, v185, v3 row_ror:8 row_mask:0xf bank_mask:0x3
	v_add_f32_dpp v3, v189, v3 quad_perm:[0,1,2,3] row_mask:0xf bank_mask:0xc
	v_cvt_pk_bf16_f32 v4, v4, v5
	v_cvt_pk_bf16_f32 v5, v6, v7
	v_cvt_pk_bf16_f32 v6, v0, v1
	v_cvt_pk_bf16_f32 v7, v2, v3
	s_nop 1
	global_store_dwordx4 v[254:255], v[4:7], off offset:256
	s_andn2_b64 vcc, exec, s[0:1]
	s_mov_b64 s[0:1], -1
	s_cbranch_vccnz .LBB0_509
	s_andn2_b64 vcc, exec, s[4:5]
	s_cbranch_vccnz .LBB0_508
	s_barrier
	s_branch .LBB0_508

; __global__ void __launch_bounds__(NWAVES * 64, 2) mk_fwd(Params P) {
	.amdhsa_kernel _Z6mk_fwd6Params
		.amdhsa_group_segment_fixed_size 0
		.amdhsa_private_segment_fixed_size 0
		.amdhsa_kernarg_size 424
		.amdhsa_user_sgpr_count 2
		.amdhsa_user_sgpr_dispatch_ptr 0
		.amdhsa_user_sgpr_queue_ptr 0
		.amdhsa_user_sgpr_kernarg_segment_ptr 1
		.amdhsa_user_sgpr_dispatch_id 0
		.amdhsa_user_sgpr_kernarg_preload_length 0
		.amdhsa_user_sgpr_kernarg_preload_offset 0
		.amdhsa_user_sgpr_private_segment_size 0
		.amdhsa_uses_dynamic_stack 0
		.amdhsa_enable_private_segment 0
		.amdhsa_system_sgpr_workgroup_id_x 1
		.amdhsa_system_sgpr_workgroup_id_y 0
		.amdhsa_system_sgpr_workgroup_id_z 0
		.amdhsa_system_sgpr_workgroup_info 0
		.amdhsa_system_vgpr_workitem_id 2
		.amdhsa_next_free_vgpr 256
		.amdhsa_next_free_sgpr 98
		.amdhsa_accum_offset 256
		.amdhsa_reserve_vcc 1
		.amdhsa_float_round_mode_32 0
		.amdhsa_float_round_mode_16_64 0
		.amdhsa_float_denorm_mode_32 3
		.amdhsa_float_denorm_mode_16_64 3
		.amdhsa_dx10_clamp 1
		.amdhsa_ieee_mode 1
		.amdhsa_fp16_overflow 0
		.amdhsa_tg_split 0
		.amdhsa_exception_fp_ieee_invalid_op 0
		.amdhsa_exception_fp_denorm_src 0
		.amdhsa_exception_fp_ieee_div_zero 0
		.amdhsa_exception_fp_ieee_overflow 0
		.amdhsa_exception_fp_ieee_underflow 0
		.amdhsa_exception_fp_ieee_inexact 0
		.amdhsa_exception_int_div_zero 0
	.end_amdhsa_kernel

; __global__ void __launch_bounds__(NWAVES * 64, 2) mk_fwd(Params P) {
amdhsa.kernels:
  - .agpr_count:     0
    .args:
      - .offset:         0
        .size:           168
        .value_kind:     by_value
      - .offset:         168
        .size:           4
        .value_kind:     hidden_block_count_x
      - .offset:         172
        .size:           4
        .value_kind:     hidden_block_count_y
      - .offset:         176
        .size:           4
        .value_kind:     hidden_block_count_z
      - .offset:         180
        .size:           2
        .value_kind:     hidden_group_size_x
      - .offset:         182
        .size:           2
        .value_kind:     hidden_group_size_y
      - .offset:         184
        .size:           2
        .value_kind:     hidden_group_size_z
      - .offset:         186
        .size:           2
        .value_kind:     hidden_remainder_x
      - .offset:         188
        .size:           2
        .value_kind:     hidden_remainder_y
      - .offset:         190
        .size:           2
        .value_kind:     hidden_remainder_z
      - .offset:         208
        .size:           8
        .value_kind:     hidden_global_offset_x
      - .offset:         216
        .size:           8
        .value_kind:     hidden_global_offset_y
      - .offset:         224
        .size:           8
        .value_kind:     hidden_global_offset_z
      - .offset:         232
        .size:           2
        .value_kind:     hidden_grid_dims
      - .offset:         256
        .size:           8
        .value_kind:     hidden_multigrid_sync_arg
      - .offset:         288
        .size:           4
        .value_kind:     hidden_dynamic_lds_size
    .group_segment_fixed_size: 0
    .kernarg_segment_align: 8
    .kernarg_segment_size: 424
    .language:       OpenCL C
    .language_version:
      - 2
      - 0
    .max_flat_workgroup_size: 512
    .name:           _Z6mk_fwd6Params
    .private_segment_fixed_size: 0
    .sgpr_count:     104
    .sgpr_spill_count: 22
    .symbol:         _Z6mk_fwd6Params.kd
    .uniform_work_group_size: 1
    .uses_dynamic_stack: false
    .vgpr_count:     256
    .vgpr_spill_count: 0
    .wavefront_size: 64
